# NSA selected + sliding-window loops on LDS-DMA staging with running buffer parity, one barrier per step
# baseline (speedup 1.0000x reference)
; template <bool FX>
; DI void nsa_tile(const Params& p, int b, int g, int tile, bf16_t* lds, const float CL) {
;     ...
;     uint32_t prev = 0xFFFFFFFFu;
;     for (int r = 0; r < 16; ++r) {
;       uint32_t mx = 0u;
; #pragma unroll
;       for (int i = 0; i < 32; ++i) {
;         uint32_t k = key[i];
;         k = (k < prev) ? k : 0u;
;         mx = (k > mx) ? k : mx;
;       }
;       uint32_t o = shxu(mx, 16, lane);
;       mx = (o > mx) ? o : mx;
;       o = shxu(mx, 32, lane);
;       mx = (o > mx) ? o : mx;
;       prev = mx;
;     }
;     sw0 = 0u; sw1 = 0u; sw2 = 0u; sw3 = 0u;
; #pragma unroll
;     for (int i = 0; i < 32; ++i) {
;       bool sel = (key[i] != 0u) && (key[i] >= prev);
;       uint32_t bit = sel ? (1u << ((i & 7) * 4 + quad)) : 0u;
;       if ((i >> 3) == 0) sw0 |= bit;
;       else if ((i >> 3) == 1) sw1 |= bit;
;       else if ((i >> 3) == 2) sw2 |= bit;
;       else sw3 |= bit;
;     }
.LBB0_662:
	v_cmp_lt_u32_e32 vcc, v4, v3
	s_add_i32 s1, s1, -1
	s_cmp_lg_u32 s1, 0
	v_cndmask_b32_e32 v33, 0, v4, vcc
	v_max_u32_e32 v36, v5, v33
	v_cmp_lt_u32_e32 vcc, v5, v3
	s_nop 1
	v_cndmask_b32_e32 v33, v33, v36, vcc
	v_max_u32_e32 v36, v34, v33
	v_cmp_lt_u32_e32 vcc, v34, v3
	s_nop 1
	v_cndmask_b32_e32 v33, v33, v36, vcc
	v_max_u32_e32 v36, v35, v33
	v_cmp_lt_u32_e32 vcc, v35, v3
	s_nop 1
	v_cndmask_b32_e32 v33, v33, v36, vcc
	v_max_u32_e32 v36, v8, v33
	v_cmp_lt_u32_e32 vcc, v8, v3
	s_nop 1
	v_cndmask_b32_e32 v33, v33, v36, vcc
	v_max_u32_e32 v36, v7, v33
	v_cmp_lt_u32_e32 vcc, v7, v3
	s_nop 1
	v_cndmask_b32_e32 v33, v33, v36, vcc
	v_max_u32_e32 v36, v12, v33
	v_cmp_lt_u32_e32 vcc, v12, v3
	s_nop 1
	v_cndmask_b32_e32 v33, v33, v36, vcc
	v_max_u32_e32 v36, v14, v33
	v_cmp_lt_u32_e32 vcc, v14, v3
	s_nop 1
	v_cndmask_b32_e32 v33, v33, v36, vcc
	v_max_u32_e32 v36, v18, v33
	v_cmp_lt_u32_e32 vcc, v18, v3
	s_nop 1
	v_cndmask_b32_e32 v33, v33, v36, vcc
	v_max_u32_e32 v36, v19, v33
	v_cmp_lt_u32_e32 vcc, v19, v3
	s_nop 1
	v_cndmask_b32_e32 v33, v33, v36, vcc
	v_max_u32_e32 v36, v23, v33
	v_cmp_lt_u32_e32 vcc, v23, v3
	s_nop 1
	v_cndmask_b32_e32 v33, v33, v36, vcc
	v_max_u32_e32 v36, v25, v33
	v_cmp_lt_u32_e32 vcc, v25, v3
	s_nop 1
	v_cndmask_b32_e32 v33, v33, v36, vcc
	v_max_u32_e32 v36, v29, v33
	v_cmp_lt_u32_e32 vcc, v29, v3
	s_nop 1
	v_cndmask_b32_e32 v33, v33, v36, vcc
	v_max_u32_e32 v36, v30, v33
	v_cmp_lt_u32_e32 vcc, v30, v3
	s_nop 1
	v_cndmask_b32_e32 v33, v33, v36, vcc
	v_max_u32_e32 v36, v32, v33
	v_cmp_lt_u32_e32 vcc, v32, v3
	s_nop 1
	v_cndmask_b32_e32 v33, v33, v36, vcc
	v_max_u32_e32 v36, v31, v33
	v_cmp_lt_u32_e32 vcc, v31, v3
	s_nop 1
	v_cndmask_b32_e32 v33, v33, v36, vcc
	v_max_u32_e32 v36, v28, v33
	v_cmp_lt_u32_e32 vcc, v28, v3
	s_nop 1
	v_cndmask_b32_e32 v33, v33, v36, vcc
	v_max_u32_e32 v36, v27, v33
	v_cmp_lt_u32_e32 vcc, v27, v3
	s_nop 1
	v_cndmask_b32_e32 v33, v33, v36, vcc
	v_max_u32_e32 v36, v26, v33
	v_cmp_lt_u32_e32 vcc, v26, v3
	s_nop 1
	v_cndmask_b32_e32 v33, v33, v36, vcc
	v_max_u32_e32 v36, v24, v33
	v_cmp_lt_u32_e32 vcc, v24, v3
	s_nop 1
	v_cndmask_b32_e32 v33, v33, v36, vcc
	v_max_u32_e32 v36, v22, v33
	v_cmp_lt_u32_e32 vcc, v22, v3
	s_nop 1
	v_cndmask_b32_e32 v33, v33, v36, vcc
	v_max_u32_e32 v36, v21, v33
	v_cmp_lt_u32_e32 vcc, v21, v3
	s_nop 1
	v_cndmask_b32_e32 v33, v33, v36, vcc
	v_max_u32_e32 v36, v20, v33
	v_cmp_lt_u32_e32 vcc, v20, v3
	s_nop 1
	v_cndmask_b32_e32 v33, v33, v36, vcc
	v_max_u32_e32 v36, v17, v33
	v_cmp_lt_u32_e32 vcc, v17, v3
	s_nop 1
	v_cndmask_b32_e32 v33, v33, v36, vcc
	v_max_u32_e32 v36, v16, v33
	v_cmp_lt_u32_e32 vcc, v16, v3
	s_nop 1
	v_cndmask_b32_e32 v33, v33, v36, vcc
	v_max_u32_e32 v36, v15, v33
	v_cmp_lt_u32_e32 vcc, v15, v3
	s_nop 1
	v_cndmask_b32_e32 v33, v33, v36, vcc
	v_max_u32_e32 v36, v13, v33
	v_cmp_lt_u32_e32 vcc, v13, v3
	s_nop 1
	v_cndmask_b32_e32 v33, v33, v36, vcc
	v_max_u32_e32 v36, v11, v33
	v_cmp_lt_u32_e32 vcc, v11, v3
	s_nop 1
	v_cndmask_b32_e32 v33, v33, v36, vcc
	v_max_u32_e32 v36, v10, v33
	v_cmp_lt_u32_e32 vcc, v10, v3
	s_nop 1
	v_cndmask_b32_e32 v33, v33, v36, vcc
	v_max_u32_e32 v36, v9, v33
	v_cmp_lt_u32_e32 vcc, v9, v3
	s_nop 1
	v_cndmask_b32_e32 v33, v33, v36, vcc
	v_max_u32_e32 v36, v6, v33
	v_cmp_lt_u32_e32 vcc, v6, v3
	s_nop 1
	v_cndmask_b32_e32 v33, v33, v36, vcc
	v_max_u32_e32 v36, v2, v33
	v_cmp_lt_u32_e32 vcc, v2, v3
	s_nop 1
	v_cndmask_b32_e32 v3, v33, v36, vcc
	ds_bpermute_b32 v33, v218, v3
	s_waitcnt lgkmcnt(0)
	v_max_u32_e32 v3, v33, v3
	ds_bpermute_b32 v33, v109, v3
	s_waitcnt lgkmcnt(0)
	v_max_u32_e32 v3, v33, v3
	s_cbranch_scc1 .LBB0_662
	v_readlane_b32 s0, v252, 37
	s_add_u32 s0, s0, s26
	v_readlane_b32 s1, v252, 38
	s_addc_u32 s1, s1, 0
	s_add_u32 s12, s18, s26
	v_cmp_ge_u32_e32 vcc, v4, v3
	s_addc_u32 s13, s19, 0
	v_lshlrev_b32_e64 v4, v131, 1
	s_and_b64 vcc, s[40:41], vcc
	v_cndmask_b32_e32 v33, 0, v4, vcc
	v_cmp_ge_u32_e32 vcc, v5, v3
	v_lshlrev_b32_e64 v36, v131, 16
	s_and_b64 vcc, s[94:95], vcc
	v_cndmask_b32_e32 v5, 0, v36, vcc
	s_movk_i32 s6, 0x100
	v_cmp_ge_u32_e32 vcc, v34, v3
	v_or_b32_e32 v5, v5, v33
	v_lshlrev_b32_e64 v33, v131, s6
	s_and_b64 vcc, s[96:97], vcc
	v_cndmask_b32_e32 v34, 0, v33, vcc
	s_movk_i32 s6, 0x1000
	v_cmp_ge_u32_e32 vcc, v35, v3
	v_lshlrev_b32_e64 v37, v131, s6
	s_and_b64 vcc, s[2:3], vcc
	v_cndmask_b32_e32 v35, 0, v37, vcc
	s_mov_b32 s2, 0x10000
	v_cmp_ge_u32_e32 vcc, v8, v3
	v_or3_b32 v5, v5, v34, v35
	v_lshlrev_b32_e64 v34, v131, s2
	s_and_b64 vcc, s[92:93], vcc
	v_cndmask_b32_e32 v8, 0, v34, vcc
	s_mov_b32 s2, 0x100000
	v_cmp_ge_u32_e32 vcc, v7, v3
	v_lshlrev_b32_e64 v35, v131, s2
	s_and_b64 vcc, s[90:91], vcc
	v_cndmask_b32_e32 v7, 0, v35, vcc
	s_mov_b32 s2, 0x1000000
	v_cmp_ge_u32_e32 vcc, v12, v3
	v_or3_b32 v5, v5, v8, v7
	v_lshlrev_b32_e64 v7, v131, s2
	s_and_b64 vcc, s[88:89], vcc
	v_cndmask_b32_e32 v8, 0, v7, vcc
	s_brev_b32 s2, 8
	v_cmp_ge_u32_e32 vcc, v14, v3
	v_lshlrev_b32_e64 v12, v131, s2
	s_and_b64 vcc, s[86:87], vcc
	v_cndmask_b32_e32 v14, 0, v12, vcc
	v_cmp_ge_u32_e32 vcc, v18, v3
	s_and_b64 vcc, s[84:85], vcc
	v_or3_b32 v5, v5, v8, v14
	v_cndmask_b32_e32 v8, 0, v4, vcc
	v_cmp_ge_u32_e32 vcc, v19, v3
	s_and_b64 vcc, s[82:83], vcc
	v_cmp_ge_u32_e64 s[2:3], v2, v3
	v_cndmask_b32_e32 v14, 0, v36, vcc
	v_cmp_ge_u32_e32 vcc, v23, v3
	s_and_b64 vcc, s[80:81], vcc
	v_or_b32_e32 v8, v14, v8
	v_cndmask_b32_e32 v14, 0, v33, vcc
	v_cmp_ge_u32_e32 vcc, v25, v3
	s_and_b64 vcc, s[78:79], vcc
	v_readlane_b32 s94, v254, 40
	v_cndmask_b32_e32 v18, 0, v37, vcc
	v_cmp_ge_u32_e32 vcc, v29, v3
	s_and_b64 vcc, s[76:77], vcc
	v_or3_b32 v8, v8, v14, v18
	v_cndmask_b32_e32 v14, 0, v34, vcc
; template <bool FX>
; DI void nsa_tile(const Params& p, int b, int g, int tile, bf16_t* lds, const float CL) {
;     ...
; #pragma unroll
;     for (int i = 0; i < 32; ++i) {
;       bool sel = (key[i] != 0u) && (key[i] >= prev);
;       uint32_t bit = sel ? (1u << ((i & 7) * 4 + quad)) : 0u;
;       if ((i >> 3) == 0) sw0 |= bit;
;       else if ((i >> 3) == 1) sw1 |= bit;
;       else if ((i >> 3) == 2) sw2 |= bit;
;       else sw3 |= bit;
;     }
;     sw0 |= shxu(sw0, 16, lane); sw0 |= shxu(sw0, 32, lane);
;     sw1 |= shxu(sw1, 16, lane); sw1 |= shxu(sw1, 32, lane);
;     sw2 |= shxu(sw2, 16, lane); sw2 |= shxu(sw2, 32, lane);
;     sw3 |= shxu(sw3, 16, lane); sw3 |= shxu(sw3, 32, lane);
;   }
;   for (int hp = 0; hp < 2; ++hp) {
; #pragma unroll
;     for (int hh = 0; hh < 2; ++hh)
; #pragma unroll
;       for (int ks = 0; ks < 2; ++ks) qf[hh][ks] = *(const bf16x8*)(ztok + C_Q + g * 256 + (hp * 2 + hh) * 64 + ks * 32 + quad * 8);
;     st_reset(st);
;     {
;       const bf16_t* kb = zb + C_KS + g * 64;
;       tile64_gload(tid, rk0, rk1, kb, ZS);
;       tile64_gload(tid, rv0, rv1, vsT, TS);
;     ...
;       const bf16_t* kb = zb + C_KW + g * 64;
;       const int s0 = (cur >= 8) ? cur - 8 : 0;
;       tile64_gload(tid, rk0, rk1, kb + (size_t)s0 * 64 * ZS, ZS);
;       tile64_gload(tid, rv0, rv1, vwT + s0 * 64, TS);
	v_cmp_ge_u32_e32 vcc, v30, v3
	s_and_b64 vcc, s[74:75], vcc
	s_mov_b32 s6, 0
	v_cndmask_b32_e32 v18, 0, v35, vcc
	v_cmp_ge_u32_e32 vcc, v32, v3
	s_and_b64 vcc, s[72:73], vcc
	v_or3_b32 v8, v8, v14, v18
	v_cndmask_b32_e32 v14, 0, v7, vcc
	v_cmp_ge_u32_e32 vcc, v31, v3
	s_and_b64 vcc, s[70:71], vcc
	s_movk_i32 s96, 0x1518
	v_cndmask_b32_e32 v18, 0, v12, vcc
	v_cmp_ge_u32_e32 vcc, v28, v3
	s_and_b64 vcc, s[68:69], vcc
	v_or3_b32 v8, v8, v14, v18
	v_cndmask_b32_e32 v14, 0, v4, vcc
	v_cmp_ge_u32_e32 vcc, v27, v3
	s_and_b64 vcc, s[66:67], vcc
	v_or_b32_e32 v184, 1, v118
	v_cndmask_b32_e32 v18, 0, v36, vcc
	v_cmp_ge_u32_e32 vcc, v26, v3
	s_and_b64 vcc, s[64:65], vcc
	v_or_b32_e32 v14, v18, v14
	v_cndmask_b32_e32 v18, 0, v33, vcc
	v_cmp_ge_u32_e32 vcc, v24, v3
	s_and_b64 vcc, s[62:63], vcc
	v_add_u32_e32 v185, v216, v113
	v_cndmask_b32_e32 v19, 0, v37, vcc
	v_cmp_ge_u32_e32 vcc, v22, v3
	s_and_b64 vcc, s[60:61], vcc
	v_or3_b32 v14, v14, v18, v19
	v_cndmask_b32_e32 v18, 0, v34, vcc
	v_cmp_ge_u32_e32 vcc, v21, v3
	s_and_b64 vcc, s[58:59], vcc
	v_readlane_b32 s95, v254, 41
	v_cndmask_b32_e32 v19, 0, v35, vcc
	v_cmp_ge_u32_e32 vcc, v20, v3
	s_and_b64 vcc, s[56:57], vcc
	v_or3_b32 v14, v14, v18, v19
	v_cndmask_b32_e32 v18, 0, v7, vcc
	v_cmp_ge_u32_e32 vcc, v17, v3
	s_and_b64 vcc, s[54:55], vcc
	v_readlane_b32 s97, v254, 42
	v_cndmask_b32_e32 v17, 0, v12, vcc
	v_cmp_ge_u32_e32 vcc, v16, v3
	s_and_b64 vcc, s[52:53], vcc
	v_or3_b32 v14, v14, v18, v17
	v_cndmask_b32_e32 v4, 0, v4, vcc
	v_cmp_ge_u32_e32 vcc, v15, v3
	s_and_b64 vcc, s[50:51], vcc
	s_nop 0
	v_cndmask_b32_e32 v15, 0, v36, vcc
	v_cmp_ge_u32_e32 vcc, v13, v3
	s_and_b64 vcc, s[48:49], vcc
	v_or_b32_e32 v4, v15, v4
	v_cndmask_b32_e32 v13, 0, v33, vcc
	v_cmp_ge_u32_e32 vcc, v11, v3
	s_and_b64 vcc, s[46:47], vcc
	s_nop 0
	v_cndmask_b32_e32 v11, 0, v37, vcc
	v_cmp_ge_u32_e32 vcc, v10, v3
	s_and_b64 vcc, s[44:45], vcc
	v_or3_b32 v4, v4, v13, v11
	v_cndmask_b32_e32 v10, 0, v34, vcc
	v_cmp_ge_u32_e32 vcc, v9, v3
	s_and_b64 vcc, s[42:43], vcc
	s_nop 0
	v_cndmask_b32_e32 v9, 0, v35, vcc
	v_cmp_ge_u32_e32 vcc, v6, v3
	s_and_b64 vcc, s[4:5], vcc
	v_or3_b32 v4, v4, v10, v9
	v_cndmask_b32_e32 v6, 0, v7, vcc
	v_cmp_ne_u32_e32 vcc, 0, v2
	ds_bpermute_b32 v2, v218, v5
	s_and_b64 vcc, vcc, s[2:3]
	v_cndmask_b32_e32 v3, 0, v12, vcc
	v_or3_b32 v3, v4, v6, v3
	ds_bpermute_b32 v7, v218, v3
	ds_bpermute_b32 v4, v218, v8
	s_waitcnt lgkmcnt(2)
	v_or_b32_e32 v2, v2, v5
	ds_bpermute_b32 v5, v218, v14
	ds_bpermute_b32 v6, v109, v2
	s_waitcnt lgkmcnt(3)
	v_or_b32_e32 v3, v7, v3
	s_waitcnt lgkmcnt(2)
	v_or_b32_e32 v4, v4, v8
	ds_bpermute_b32 v7, v109, v3
	s_waitcnt lgkmcnt(2)
	v_or_b32_e32 v5, v5, v14
	ds_bpermute_b32 v8, v109, v4
	ds_bpermute_b32 v9, v109, v5
	v_readlane_b32 s2, v255, 0
	s_lshl_b32 s2, s2, 1
	v_readlane_b32 s3, v254, 60
	s_add_u32 s30, s3, s2
	v_readlane_b32 s2, v254, 61
	s_movk_i32 s4, 0x1518
	s_addc_u32 s31, s2, 0
	v_mad_i64_i32 v[130:131], s[2:3], v106, s4, 0
	s_waitcnt lgkmcnt(3)
	v_or_b32_e32 v180, v2, v6
	s_waitcnt lgkmcnt(2)
	v_or_b32_e32 v183, v3, v7
	v_lshlrev_b64 v[2:3], 1, v[130:131]
	s_waitcnt lgkmcnt(1)
	v_or_b32_e32 v181, v4, v8
	s_waitcnt lgkmcnt(0)
	v_or_b32_e32 v182, v5, v9
	v_lshl_add_u64 v[4:5], s[30:31], 0, v[2:3]
	v_mad_i64_i32 v[134:135], s[2:3], v108, s4, 0
	v_lshl_add_u64 v[132:133], v[4:5], 0, v[0:1]
	v_lshlrev_b64 v[4:5], 1, v[134:135]
	s_movk_i32 s4, 0x2040
	v_lshl_add_u64 v[6:7], s[30:31], 0, v[4:5]
	v_mad_i64_i32 v[138:139], s[2:3], v106, s4, 0
	v_lshl_add_u64 v[136:137], v[6:7], 0, v[0:1]
	v_lshlrev_b64 v[6:7], 1, v[138:139]
	v_lshl_add_u64 v[8:9], s[12:13], 0, v[6:7]
	v_mad_i64_i32 v[142:143], s[2:3], v108, s4, 0
	v_lshl_add_u64 v[140:141], v[8:9], 0, v[0:1]
	v_lshlrev_b64 v[8:9], 1, v[142:143]
	v_lshl_add_u64 v[10:11], s[12:13], 0, v[8:9]
	v_sub_u32_e64 v12, s25, 8 clamp
	s_mov_b32 s2, 0xa8c00
	v_lshl_add_u64 v[144:145], v[10:11], 0, v[0:1]
	v_mul_hi_u32 v11, v12, s2
	v_mul_lo_u32 v10, v12, s2
	v_lshl_add_u64 v[10:11], s[30:31], 0, v[10:11]
	v_lshl_add_u64 v[2:3], v[10:11], 0, v[2:3]
	v_lshl_add_u64 v[146:147], v[2:3], 0, v[0:1]
	v_lshl_add_u64 v[2:3], v[10:11], 0, v[4:5]
	v_lshl_add_u64 v[148:149], v[2:3], 0, v[0:1]
	v_lshlrev_b32_e32 v2, 6, v12
	v_mov_b32_e32 v3, v1
	v_lshlrev_b64 v[2:3], 1, v[2:3]
	v_lshl_add_u64 v[2:3], s[0:1], 0, v[2:3]
	v_lshl_add_u64 v[4:5], v[2:3], 0, v[6:7]
	v_lshl_add_u64 v[2:3], v[2:3], 0, v[8:9]
	v_lshl_add_u64 v[152:153], v[2:3], 0, v[0:1]
	v_mov_b64_e32 v[2:3], s[10:11]
	v_lshl_add_u64 v[150:151], v[4:5], 0, v[0:1]
	v_mad_i64_i32 v[4:5], s[2:3], v108, s35, v[2:3]
	v_mad_i64_i32 v[2:3], s[2:3], v106, s35, v[2:3]
	s_min_u32 s2, s25, 8
	v_readlane_b32 s4, v254, 62
	s_sub_i32 s26, s25, s2
	v_lshl_add_u64 v[4:5], v[4:5], 0, v[110:111]
	v_readlane_b32 s5, v254, 63
	v_lshl_add_u64 v[2:3], v[2:3], 0, v[110:111]
	s_add_i32 s26, s26, 1
	s_lshl_b32 s2, s2, 6
	v_lshl_add_u64 v[154:155], s[4:5], 0, v[4:5]
	v_lshl_add_u64 v[156:157], s[4:5], 0, v[2:3]
	s_lshl_b32 s27, s26, 6
	v_add3_u32 v186, s2, v215, v113
	s_mov_b64 s[2:3], -1
	v_and_b32_e32 v202, 7, v196
	v_bfe_u32 v218, v196, 4, 3
	v_xor_b32_e32 v202, v202, v218
	v_lshlrev_b32_e32 v202, 4, v202
	v_mov_b32_e32 v203, 0
	v_sub_u32_e32 v218, v202, v0
	v_ashrrev_i32_e32 v219, 31, v218
	v_readfirstlane_b32 s77, v196
	s_lshr_b32 s76, s77, 8
	s_lshl_b32 s76, s76, 16
	s_bfe_u32 s77, s77, 0x20006
	s_lshl_b32 s77, s77, 10
	s_or_b32 s76, s76, s77
	s_or_b32 s76, s76, 0xc000
	s_mov_b32 s75, 0xc000
	s_mov_b32 s79, 0
	v_xor_b32_e32 v188, 0xc000, v188
	v_xor_b32_e32 v189, 0xc000, v189
	v_xor_b32_e32 v190, 0xc000, v190
	v_xor_b32_e32 v191, 0xc000, v191
	v_xor_b32_e32 v207, 0xc000, v207
	v_xor_b32_e32 v208, 0xc000, v208
	v_xor_b32_e32 v209, 0xc000, v209
	v_xor_b32_e32 v210, 0xc000, v210
	v_xor_b32_e32 v211, 0xc000, v211
	v_xor_b32_e32 v212, 0xc000, v212
	v_xor_b32_e32 v213, 0xc000, v213
	v_xor_b32_e32 v214, 0xc000, v214
	s_branch .LBB0_665
.Lnsa_tile_exit:
	v_xor_b32_e32 v188, s75, v188
	v_xor_b32_e32 v189, s75, v189
	v_xor_b32_e32 v190, s75, v190
	v_xor_b32_e32 v191, s75, v191
	v_xor_b32_e32 v207, s75, v207
	v_xor_b32_e32 v208, s75, v208
	v_xor_b32_e32 v209, s75, v209
	v_xor_b32_e32 v210, s75, v210
	v_xor_b32_e32 v211, s75, v211
	v_xor_b32_e32 v212, s75, v212
	v_xor_b32_e32 v213, s75, v213
	v_xor_b32_e32 v214, s75, v214
	s_branch .LBB0_358

; template <bool FX>
; DI void nsa_tile(const Params& p, int b, int g, int tile, bf16_t* lds, const float CL) {
;     ...
;   for (int hp = 0; hp < 2; ++hp) {
; #pragma unroll
;     for (int hh = 0; hh < 2; ++hh)
; #pragma unroll
;       for (int ks = 0; ks < 2; ++ks) qf[hh][ks] = *(const bf16x8*)(ztok + C_Q + g * 256 + (hp * 2 + hh) * 64 + ks * 32 + quad * 8);
;     st_reset(st);
;     {
;       const bf16_t* kb = zb + C_KS + g * 64;
;       tile64_gload(tid, rk0, rk1, kb, ZS);
;       tile64_gload(tid, rv0, rv1, vsT, TS);
.LBB0_665:
	s_lshl_b32 s28, s6, 8
	v_lshl_add_u64 v[14:15], v[116:117], 0, s[28:29]
	global_load_dwordx4 v[2:5], v[14:15], off
	global_load_dwordx4 v[6:9], v[14:15], off offset:64
	global_load_dwordx4 v[10:13], v[14:15], off offset:128
	s_nop 0
	global_load_dwordx4 v[14:17], v[14:15], off offset:192
	s_nop 0
	s_movk_i32 s78, 0x600
	v_lshl_add_u64 v[58:59], v[132:133], 0, v[218:219]
	v_lshl_add_u64 v[60:61], v[136:137], 0, v[218:219]
	v_lshl_add_u64 v[62:63], v[140:141], 0, v[218:219]
	v_lshl_add_u64 v[64:65], v[144:145], 0, v[218:219]
	v_lshl_add_u64 v[58:59], v[58:59], 0, s[78:79]
	v_lshl_add_u64 v[60:61], v[60:61], 0, s[78:79]
	s_mov_b32 m0, s76
	s_nop 0
	global_load_lds_dwordx4 v[58:59], off
	s_add_u32 m0, s76, 0x1000
	s_nop 0
	global_load_lds_dwordx4 v[60:61], off
	s_add_u32 m0, s76, 0x2000
	s_nop 0
	global_load_lds_dwordx4 v[62:63], off
	s_add_u32 m0, s76, 0x3000
	s_nop 0
	global_load_lds_dwordx4 v[64:65], off
	s_xor_b32 s76, s76, 0xc000
	v_mov_b32_e32 v54, v1
	v_mov_b32_e32 v55, v1
	v_mov_b32_e32 v56, v1
	v_mov_b32_e32 v57, v1
	v_mov_b64_e32 v[46:47], v[54:55]
	v_mov_b64_e32 v[50:51], v[54:55]
	v_mov_b64_e32 v[42:43], v[54:55]
	v_mov_b64_e32 v[38:39], v[54:55]
	v_mov_b64_e32 v[34:35], v[54:55]
	v_mov_b64_e32 v[30:31], v[54:55]
	v_mov_b64_e32 v[26:27], v[54:55]
	v_mov_b64_e32 v[22:23], v[54:55]
	v_mov_b64_e32 v[18:19], v[54:55]
	s_xor_b64 s[36:37], s[2:3], -1
	s_lshl_b32 s7, s6, 7
	s_mov_b32 s28, 64
	s_mov_b32 s68, -1
	v_mov_b32_e32 v187, v185
	v_lshl_add_u64 v[158:159], v[156:157], 0, v[218:219]
	v_lshl_add_u64 v[160:161], v[154:155], 0, v[218:219]
	v_mov_b64_e32 v[48:49], v[56:57]
	v_mov_b64_e32 v[52:53], v[56:57]
	v_mov_b64_e32 v[44:45], v[56:57]
	v_mov_b64_e32 v[40:41], v[56:57]
	v_mov_b64_e32 v[36:37], v[56:57]
	v_mov_b64_e32 v[32:33], v[56:57]
	v_mov_b64_e32 v[28:29], v[56:57]
	v_mov_b64_e32 v[24:25], v[56:57]
	v_mov_b64_e32 v[20:21], v[56:57]
	s_branch .LBB0_668

; DI float bflo(unsigned u) { return __uint_as_float(u << 16); }
; DI float bfhi(unsigned u) { return __uint_as_float(u & 0xffff0000u); }
; template <bool FIRST>
; DI void nsa_flush(const int quad, bf16_t* optr, const AttnSt& st, const float (&sc)[2]) {
; #pragma unroll
;   for (int h = 0; h < 2; ++h)
; #pragma unroll
;     for (int dt = 0; dt < 4; ++dt) {
;       uint2* q = (uint2*)(optr + h * 64 + dt * 16 + quad * 4);
;       f32x4 o = st.O[h][dt] * sc[h];
;       if (!FIRST) {
;         uint2 pv = *q;
;         o[0] += bflo(pv.x); o[1] += bfhi(pv.x); o[2] += bflo(pv.y); o[3] += bfhi(pv.y);
;       }
;       uint2 u;
;       u.x = pack2(o[0], o[1]);
;       u.y = pack2(o[2], o[3]);
;       *q = u;
;     }
; }
; template <bool FX>
; DI void nsa_tile(const Params& p, int b, int g, int tile, bf16_t* lds, const float CL) {
;     ...
;     st_reset(st);
;     {
;       const bf16_t* kb = zb + C_KW + g * 64;
;       const int s0 = (cur >= 8) ? cur - 8 : 0;
;       tile64_gload(tid, rk0, rk1, kb + (size_t)s0 * 64 * ZS, ZS);
;       tile64_gload(tid, rv0, rv1, vwT + s0 * 64, TS);
.LBB0_679:
	s_or_b64 exec, exec, s[2:3]
	s_lshl_b32 s28, s7, 1
	v_lshl_add_u64 v[158:159], v[128:129], 0, s[28:29]
	global_load_dwordx2 v[46:47], v[158:159], off
	v_mov_b32_e32 v49, v48
	v_mov_b32_e32 v178, v186
	s_mov_b32 s71, s26
	s_mov_b32 s28, s27
	s_waitcnt vmcnt(0)
	v_lshlrev_b32_e32 v54, 16, v46
	v_and_b32_e32 v55, 0xffff0000, v46
	v_lshlrev_b32_e32 v46, 16, v47
	v_and_b32_e32 v47, 0xffff0000, v47
	v_pk_fma_f32 v[50:51], v[50:51], v[56:57], v[54:55]
	v_pk_fma_f32 v[46:47], v[52:53], v[58:59], v[46:47]
	v_cvt_pk_bf16_f32 v50, v50, v51
	v_cvt_pk_bf16_f32 v51, v46, v47
	global_load_dwordx2 v[46:47], v[158:159], off offset:32
	s_nop 0
	global_store_dwordx2 v[158:159], v[50:51], off
	s_waitcnt vmcnt(1)
	v_lshlrev_b32_e32 v50, 16, v46
	v_and_b32_e32 v51, 0xffff0000, v46
	v_lshlrev_b32_e32 v46, 16, v47
	v_and_b32_e32 v47, 0xffff0000, v47
	v_pk_fma_f32 v[42:43], v[42:43], v[56:57], v[50:51]
	v_pk_fma_f32 v[44:45], v[44:45], v[58:59], v[46:47]
	v_cvt_pk_bf16_f32 v42, v42, v43
	v_cvt_pk_bf16_f32 v43, v44, v45
	global_store_dwordx2 v[158:159], v[42:43], off offset:32
	global_load_dwordx2 v[42:43], v[158:159], off offset:64
	v_mov_b32_e32 v46, 0
	v_mov_b32_e32 v47, v46
	v_mov_b32_e32 v54, v46
	v_mov_b32_e32 v55, v46
	v_mov_b32_e32 v50, v46
	v_mov_b32_e32 v51, v46
	v_mov_b32_e32 v52, v46
	v_mov_b32_e32 v53, v46
	s_waitcnt vmcnt(0)
	v_lshlrev_b32_e32 v44, 16, v42
	v_and_b32_e32 v45, 0xffff0000, v42
	v_lshlrev_b32_e32 v42, 16, v43
	v_and_b32_e32 v43, 0xffff0000, v43
	v_pk_fma_f32 v[38:39], v[38:39], v[56:57], v[44:45]
	v_pk_fma_f32 v[40:41], v[40:41], v[58:59], v[42:43]
	v_cvt_pk_bf16_f32 v38, v38, v39
	v_cvt_pk_bf16_f32 v39, v40, v41
	global_store_dwordx2 v[158:159], v[38:39], off offset:64
	global_load_dwordx2 v[38:39], v[158:159], off offset:96
	v_mov_b32_e32 v42, v46
	v_mov_b32_e32 v43, v46
	v_mov_b32_e32 v44, v46
	v_mov_b32_e32 v45, v46
	s_waitcnt vmcnt(0)
	v_lshlrev_b32_e32 v40, 16, v38
	v_and_b32_e32 v41, 0xffff0000, v38
	v_lshlrev_b32_e32 v38, 16, v39
	v_and_b32_e32 v39, 0xffff0000, v39
	v_pk_fma_f32 v[34:35], v[34:35], v[56:57], v[40:41]
	v_pk_fma_f32 v[36:37], v[36:37], v[58:59], v[38:39]
	v_cvt_pk_bf16_f32 v34, v34, v35
	v_cvt_pk_bf16_f32 v35, v36, v37
	global_load_dwordx2 v[36:37], v[158:159], off offset:128
	v_mov_b32_e32 v40, v46
	global_store_dwordx2 v[158:159], v[34:35], off offset:96
	v_mov_b32_e32 v34, v48
	v_mov_b32_e32 v35, v48
	v_mov_b32_e32 v41, v46
	v_mov_b32_e32 v56, v46
	v_mov_b32_e32 v57, v46
	s_waitcnt vmcnt(1)
	v_lshlrev_b32_e32 v38, 16, v36
	v_and_b32_e32 v39, 0xffff0000, v36
	v_lshlrev_b32_e32 v36, 16, v37
	v_and_b32_e32 v37, 0xffff0000, v37
	v_pk_fma_f32 v[30:31], v[30:31], v[34:35], v[38:39]
	v_pk_fma_f32 v[32:33], v[32:33], v[48:49], v[36:37]
	v_cvt_pk_bf16_f32 v30, v30, v31
	v_cvt_pk_bf16_f32 v31, v32, v33
	global_store_dwordx2 v[158:159], v[30:31], off offset:128
	global_load_dwordx2 v[30:31], v[158:159], off offset:160
	v_mov_b32_e32 v38, v46
	v_mov_b32_e32 v39, v46
	v_mov_b32_e32 v36, v46
	v_mov_b32_e32 v37, v46
	s_waitcnt vmcnt(0)
	v_lshlrev_b32_e32 v32, 16, v30
	v_and_b32_e32 v33, 0xffff0000, v30
	v_lshlrev_b32_e32 v30, 16, v31
	v_and_b32_e32 v31, 0xffff0000, v31
	v_pk_fma_f32 v[26:27], v[26:27], v[34:35], v[32:33]
	v_pk_fma_f32 v[28:29], v[28:29], v[48:49], v[30:31]
	v_cvt_pk_bf16_f32 v26, v26, v27
	v_cvt_pk_bf16_f32 v27, v28, v29
	global_store_dwordx2 v[158:159], v[26:27], off offset:160
	global_load_dwordx2 v[26:27], v[158:159], off offset:192
	v_mov_b32_e32 v30, v46
	v_mov_b32_e32 v31, v46
	v_mov_b32_e32 v32, v46
	v_mov_b32_e32 v33, v46
	s_waitcnt vmcnt(0)
	v_lshlrev_b32_e32 v28, 16, v26
	v_and_b32_e32 v29, 0xffff0000, v26
	v_lshlrev_b32_e32 v26, 16, v27
	v_and_b32_e32 v27, 0xffff0000, v27
	v_pk_fma_f32 v[22:23], v[22:23], v[34:35], v[28:29]
	v_pk_fma_f32 v[24:25], v[24:25], v[48:49], v[26:27]
	v_cvt_pk_bf16_f32 v22, v22, v23
	v_cvt_pk_bf16_f32 v23, v24, v25
	global_store_dwordx2 v[158:159], v[22:23], off offset:192
	global_load_dwordx2 v[22:23], v[158:159], off offset:224
	v_mov_b32_e32 v26, v46
	v_mov_b32_e32 v27, v46
	v_mov_b32_e32 v28, v46
	v_mov_b32_e32 v29, v46
	s_waitcnt vmcnt(0)
	v_lshlrev_b32_e32 v24, 16, v22
	v_and_b32_e32 v25, 0xffff0000, v22
	v_lshlrev_b32_e32 v22, 16, v23
	v_and_b32_e32 v23, 0xffff0000, v23
	v_pk_fma_f32 v[18:19], v[18:19], v[34:35], v[24:25]
	v_pk_fma_f32 v[20:21], v[20:21], v[48:49], v[22:23]
	v_cvt_pk_bf16_f32 v18, v18, v19
	v_cvt_pk_bf16_f32 v19, v20, v21
	global_store_dwordx2 v[158:159], v[18:19], off offset:224
	s_movk_i32 s78, 0x800
	v_lshl_add_u64 v[58:59], v[146:147], 0, v[218:219]
	v_lshl_add_u64 v[60:61], v[148:149], 0, v[218:219]
	v_lshl_add_u64 v[62:63], v[150:151], 0, v[218:219]
	v_lshl_add_u64 v[64:65], v[152:153], 0, v[218:219]
	v_lshl_add_u64 v[58:59], v[58:59], 0, s[78:79]
	v_lshl_add_u64 v[60:61], v[60:61], 0, s[78:79]
	s_mov_b32 m0, s76
	s_nop 0
	global_load_lds_dwordx4 v[58:59], off
	s_add_u32 m0, s76, 0x1000
	s_nop 0
	global_load_lds_dwordx4 v[60:61], off
	s_add_u32 m0, s76, 0x2000
	s_nop 0
	global_load_lds_dwordx4 v[62:63], off
	s_add_u32 m0, s76, 0x3000
	s_nop 0
	global_load_lds_dwordx4 v[64:65], off
	s_xor_b32 s76, s76, 0xc000
	v_mov_b32_e32 v48, v46
	v_mov_b32_e32 v49, v46
	v_mov_b32_e32 v34, v46
	v_mov_b32_e32 v35, v46
	v_mov_b32_e32 v22, v46
	v_mov_b32_e32 v23, v46
	v_mov_b32_e32 v24, v46
	v_mov_b32_e32 v25, v46
	v_mov_b32_e32 v18, v46
	v_mov_b32_e32 v19, v46
	v_mov_b32_e32 v20, v46
	v_mov_b32_e32 v21, v46
	s_branch .LBB0_681
; DI f32x4 mfma16(bf16x8 a, bf16x8 b, f32x4 c) { return __builtin_amdgcn_mfma_f32_16x16x32_bf16(a, b, c, 0, 0, 0); }
; template <int MODE, bool FX>
; DI void attn_compute(const int lane, const bf16_t* Ks, const bf16_t* Vs, const bf16x8 (&qf)[2][2], AttnSt& st, const float (&invl)[2],
;                      int lo, int hi, float (&impA)[4], float (&impE)[4], const float CL) {
;     ...
;   if (MODE != 0) {
; #pragma unroll
;     for (int dt = 0; dt < 4; ++dt) {
;       const int row = dt * 16 + col;
;       const int sw = (row >> 1) & 7;
; #pragma unroll
;       for (int c = 0; c < 2; ++c) {
;         uint2 a = *(const uint2*)(Vs + row * 64 + (((4 * c + (quad >> 1)) ^ sw) << 3) + (quad & 1) * 4);
;         uint2 b = *(const uint2*)(Vs + row * 64 + (((4 * c + 2 + (quad >> 1)) ^ sw) << 3) + (quad & 1) * 4);
;         bf16x8 vf = mk8(a.x, a.y, b.x, b.y);
; #pragma unroll
;         for (int hh = 0; hh < 2; ++hh) st.O[hh][dt] = mfma16(vf, pf[hh][c], st.O[hh][dt]);
;       }
;     }
;     if (FX && MODE == 2) {
;       const bf16x8 ones = mk8(0x3F803F80u, 0x3F803F80u, 0x3F803F80u, 0x3F803F80u);
; #pragma unroll
;       for (int c = 0; c < 2; ++c)
; #pragma unroll
;         for (int hh = 0; hh < 2; ++hh) st.L[hh] = mfma16(ones, pf[hh][c], st.L[hh]);
;     }
; template <bool FX>
; DI void nsa_tile(const Params& p, int b, int g, int tile, bf16_t* lds, const float CL) {
;     ...
;       for (int s = s0; s <= cur; ++s) {
;         __syncthreads();
;         tile64_sstore(tid, Ks, rk0, rk1);
;         tile64_sstore(tid, Vs, rv0, rv1);
;         __syncthreads();
;         if (s < cur) {
;           tile64_gload(tid, rk0, rk1, kb + (size_t)(s + 1) * 64 * ZS, ZS);
;           tile64_gload(tid, rv0, rv1, vwT + (s + 1) * 64, TS);
;         }
.LBB0_680:
	ds_read2st64_b64 v[90:93], v207 offset0:16 offset1:20
	ds_read2st64_b64 v[94:97], v208 offset0:16 offset1:20
	v_cvt_pk_bf16_f32 v82, v160, v161
	v_cvt_pk_bf16_f32 v83, v164, v165
	v_cvt_pk_bf16_f32 v84, v166, v167
	s_waitcnt lgkmcnt(1)
	v_mov_b32_e32 v98, v90
	v_mov_b32_e32 v99, v91
	s_waitcnt lgkmcnt(0)
	v_mov_b32_e32 v100, v94
	v_mov_b32_e32 v101, v95
	v_cvt_pk_bf16_f32 v85, v168, v169
	v_mov_b32_e32 v94, v92
	v_mfma_f32_16x16x32_bf16 v[46:49], v[98:101], v[74:77], v[46:49]
	v_mov_b32_e32 v95, v93
	v_cvt_pk_bf16_f32 v86, v170, v171
	v_cvt_pk_bf16_f32 v87, v172, v173
	v_mfma_f32_16x16x32_bf16 v[30:33], v[98:101], v[82:85], v[30:33]
	ds_read2st64_b64 v[98:101], v209 offset0:16 offset1:20
	ds_read2st64_b64 v[102:105], v210 offset0:16 offset1:20
	ds_read_b64 v[90:91], v207 offset:12288
	ds_read_b64 v[92:93], v208 offset:12288
	v_cvt_pk_bf16_f32 v88, v174, v175
	s_waitcnt lgkmcnt(0)
	v_mfma_f32_16x16x32_bf16 v[38:41], v[90:93], v[74:77], v[38:41]
	v_cvt_pk_bf16_f32 v89, v176, v177
	s_mov_b32 s10, s8
	s_mov_b32 s11, s8
	v_mfma_f32_16x16x32_bf16 v[22:25], v[90:93], v[82:85], v[22:25]
	ds_read_b64 v[90:91], v209 offset:12288
	ds_read_b64 v[92:93], v210 offset:12288
	s_mov_b32 s9, s8
	v_mov_b32_e32 v106, v98
	s_waitcnt lgkmcnt(0)
	v_mfma_f32_16x16x32_bf16 v[38:41], v[90:93], v[78:81], v[38:41]
	v_mov_b32_e32 v107, v99
	v_mov_b32_e32 v108, v102
	v_mov_b32_e32 v109, v103
	v_mfma_f32_16x16x32_bf16 v[22:25], v[90:93], v[86:89], v[22:25]
	ds_read_b64 v[90:91], v211 offset:8192
	ds_read_b64 v[92:93], v212 offset:8192
	v_mov_b32_e32 v102, v100
	v_mov_b32_e32 v103, v101
	s_waitcnt lgkmcnt(0)
	v_mfma_f32_16x16x32_bf16 v[34:37], v[90:93], v[74:77], v[34:37]
	s_add_i32 s28, s28, 64
	s_add_i32 s71, s71, 1
	v_subrev_u32_e32 v178, 64, v178
	v_mfma_f32_16x16x32_bf16 v[18:21], v[90:93], v[82:85], v[18:21]
	ds_read_b64 v[90:91], v213 offset:8192
	ds_read_b64 v[92:93], v214 offset:8192
	s_xor_b32 s75, s75, 0xc000
	s_cmp_ge_u32 s72, s25
	s_waitcnt lgkmcnt(0)
	v_mfma_f32_16x16x32_bf16 v[34:37], v[90:93], v[78:81], v[34:37]
	v_mfma_f32_16x16x32_bf16 v[18:21], v[90:93], v[86:89], v[18:21]
	v_mov_b64_e32 v[92:93], s[10:11]
	v_mov_b64_e32 v[90:91], s[8:9]
	v_mfma_f32_16x16x32_bf16 v[42:45], v[94:97], v[74:77], v[42:45]
	v_mfma_f32_16x16x32_bf16 v[26:29], v[94:97], v[82:85], v[26:29]
	v_mfma_f32_16x16x32_bf16 v[54:57], v[90:93], v[74:77], v[54:57]
	v_mfma_f32_16x16x32_bf16 v[50:53], v[90:93], v[82:85], v[50:53]
	v_mfma_f32_16x16x32_bf16 v[46:49], v[106:109], v[78:81], v[46:49]
	v_mfma_f32_16x16x32_bf16 v[30:33], v[106:109], v[86:89], v[30:33]
	v_mfma_f32_16x16x32_bf16 v[42:45], v[102:105], v[78:81], v[42:45]
	v_mfma_f32_16x16x32_bf16 v[26:29], v[102:105], v[86:89], v[26:29]
	v_mfma_f32_16x16x32_bf16 v[54:57], v[90:93], v[78:81], v[54:57]
	v_mfma_f32_16x16x32_bf16 v[50:53], v[90:93], v[86:89], v[50:53]
	v_xor_b32_e32 v188, 0xc000, v188
	v_xor_b32_e32 v189, 0xc000, v189
	v_xor_b32_e32 v190, 0xc000, v190
	v_xor_b32_e32 v191, 0xc000, v191
	v_xor_b32_e32 v207, 0xc000, v207
	v_xor_b32_e32 v208, 0xc000, v208
	v_xor_b32_e32 v209, 0xc000, v209
	v_xor_b32_e32 v210, 0xc000, v210
	v_xor_b32_e32 v211, 0xc000, v211
	v_xor_b32_e32 v212, 0xc000, v212
	v_xor_b32_e32 v213, 0xc000, v213
	v_xor_b32_e32 v214, 0xc000, v214
	s_cbranch_scc1 .LBB0_687
.LBB0_681:
	s_add_i32 s72, s71, -1
	s_waitcnt vmcnt(0)
	s_barrier
	s_cmp_ge_u32 s72, s25
	s_cbranch_scc1 .LBB0_683
	s_mul_i32 s2, s71, 0xa8c00
	s_mul_hi_u32 s3, s71, 0xa8c00
	s_add_u32 s2, s30, s2
	s_addc_u32 s3, s31, s3
	v_lshl_add_u64 v[58:59], v[130:131], 1, s[2:3]
	v_lshl_add_u64 v[60:61], v[134:135], 1, s[2:3]
	s_lshl_b64 s[2:3], s[28:29], 1
	s_add_u32 s2, s0, s2
	s_addc_u32 s3, s1, s3
	v_lshl_add_u64 v[66:67], v[138:139], 1, s[2:3]
	v_lshl_add_u64 v[68:69], v[142:143], 1, s[2:3]
	s_movk_i32 s78, 0x800
	v_lshl_add_u64 v[58:59], v[58:59], 0, v[202:203]
	v_lshl_add_u64 v[62:63], v[60:61], 0, v[202:203]
	v_lshl_add_u64 v[66:67], v[66:67], 0, v[202:203]
	v_lshl_add_u64 v[70:71], v[68:69], 0, v[202:203]
	v_lshl_add_u64 v[58:59], v[58:59], 0, s[78:79]
	v_lshl_add_u64 v[62:63], v[62:63], 0, s[78:79]
	s_mov_b32 m0, s76
	s_nop 0
	global_load_lds_dwordx4 v[58:59], off
	s_add_u32 m0, s76, 0x1000
	s_nop 0
	global_load_lds_dwordx4 v[62:63], off
	s_add_u32 m0, s76, 0x2000
	s_nop 0
	global_load_lds_dwordx4 v[66:67], off
	s_add_u32 m0, s76, 0x3000
	s_nop 0
	global_load_lds_dwordx4 v[70:71], off
	s_xor_b32 s76, s76, 0xc000
